# EPI_RES epilogue of FFN-down s=0: residual loads batched 8-deep per pass
# speedup vs baseline: 1.0102x; 1.0102x over previous
; template <int EPI, int MI>
; DI void gemm_tile(const GemmDesc& g, int tm, int tn, char* smem) {
;     ...
;   } else if (EPI == EPI_RES) {
;     float* es = (float*)smem;
;     const int c4 = (tid & 31) * 4;
;     const int rgA = m0 < LAT ? (m0 >> 11) : 8;
;     const int mlast = m0 + BM - 1;
;     const int rgB = mlast < LAT ? (mlast >> 11) : 8;
;     const f32x4v m4a = *(const f32x4v*)(g.mod + (size_t)rgA * 9216 + g.gidx * 1024 + n0 + c4);
;     const f32x4v m4b = *(const f32x4v*)(g.mod + (size_t)rgB * 9216 + g.gidx * 1024 + n0 + c4);
; #pragma unroll
;     for (int mi = 0; mi < MI; ++mi) {
; #pragma unroll
;       for (int ni = 0; ni < 2; ++ni)
; #pragma unroll
;         for (int i = 0; i < 16; ++i) {
;           const int lrow = wm * 32 + (i & 3) + 8 * (i >> 2) + 4 * hh;
;           es[lrow * 128 + wn * 64 + ni * 32 + r] = acc[mi][ni][i];
;         }
;       __syncthreads();
; #pragma unroll 4
;       for (int j = 0; j < 8; ++j) {
;         const int lrow = (tid >> 5) + 8 * j;
;         const int grow = m0 + (lrow >> 5) * (32 * MI) + mi * 32 + (lrow & 31);
;         const f32x4v a4 = *(const f32x4v*)(es + lrow * 128 + c4);
;         const int rg = grow < LAT ? (grow >> 11) : 8;
;         const f32x4v m4 = rg == rgA ? m4a : m4b;
;         float* rp = (grow < LAT ? g.xres + (size_t)grow * 1024 : g.hres + (size_t)(grow - LAT) * 1024) + n0 + c4;
;         f32x4v x4 = *(const f32x4v*)rp;
;         x4 += (m4 * a4) * g.coef;
;         *(f32x4v*)rp = x4;
;       }
.LBB0_258:
	s_ashr_i32 s4, s43, 11
	s_cmpk_lt_i32 s1, 0x56
	s_cselect_b32 s15, s4, 8
	s_add_i32 s4, s43, 0xbf
	s_ashr_i32 s4, s4, 11
	s_cmpk_lt_i32 s1, 0x55
	s_cselect_b32 s16, s4, 8
	s_mul_i32 s4, s15, 0x9000
	s_mul_hi_i32 s1, s15, 0x9000
	s_add_u32 s17, s20, s4
	s_addc_u32 s18, s38, s1
	s_ashr_i32 s1, s0, 31
	v_lshlrev_b32_e32 v98, 2, v97
	s_lshl_b64 s[4:5], s[0:1], 2
	v_and_b32_e32 v106, 0x7c, v98
	s_add_u32 s0, s17, s4
	s_addc_u32 s1, s18, s5
	v_lshlrev_b32_e32 v102, 2, v106
	global_load_dwordx4 v[98:101], v102, s[0:1]
	s_mul_hi_i32 s0, s16, 0x9000
	s_mul_i32 s16, s16, 0x9000
	s_add_u32 s1, s20, s16
	s_addc_u32 s16, s38, s0
	s_add_u32 s0, s1, s4
	s_addc_u32 s1, s16, s5
	global_load_dwordx4 v[102:105], v102, s[0:1]
	v_and_b32_e32 v107, 64, v97
	v_lshlrev_b32_e32 v115, 11, v115
	v_lshlrev_b32_e32 v107, 2, v107
	v_lshlrev_b32_e32 v109, 14, v109
	v_add3_u32 v107, 0, v115, v107
	v_lshlrev_b32_e32 v115, 2, v108
	v_ashrrev_i32_e32 v97, 5, v97
	v_add3_u32 v107, v107, v115, v109
	ds_write2_b32 v107, v80, v64 offset1:32
	ds_write2_b32 v107, v81, v65 offset0:128 offset1:160
	v_add_u32_e32 v80, 0x400, v107
	v_add_u32_e32 v64, 8, v97
	ds_write2_b32 v80, v82, v66 offset1:32
	ds_write2_b32 v80, v83, v67 offset0:128 offset1:160
	v_add_u32_e32 v81, 0x1000, v107
	v_add_u32_e32 v82, 0x1400, v107
	v_and_b32_e32 v67, 31, v64
	v_add_u32_e32 v64, 24, v97
	ds_write2_b32 v81, v84, v68 offset1:32
	ds_write2_b32 v81, v85, v69 offset0:128 offset1:160
	ds_write2_b32 v82, v86, v70 offset1:32
	ds_write2_b32 v82, v87, v71 offset0:128 offset1:160
	v_add_u32_e32 v71, 0x2000, v107
	v_and_b32_e32 v69, 31, v64
	v_lshlrev_b32_e32 v64, 4, v108
	ds_write2_b32 v71, v88, v72 offset1:32
	ds_write2_b32 v71, v89, v73 offset0:128 offset1:160
	v_add_u32_e32 v72, 0x2400, v107
	v_lshl_or_b32 v64, v97, 9, v64
	ds_write2_b32 v72, v90, v74 offset1:32
	ds_write2_b32 v72, v91, v75 offset0:128 offset1:160
	v_add_u32_e32 v73, 0x3000, v107
	v_add_u32_e32 v74, 0x3400, v107
	v_and_b32_e32 v66, 31, v97
	v_bitop3_b32 v68, v97, 16, 31 bitop3:0x6c
	v_add_u32_e32 v70, 0, v64
	s_mov_b32 s16, 0
	v_mov_b32_e32 v75, v97
	ds_write2_b32 v73, v92, v76 offset1:32
	ds_write2_b32 v73, v93, v77 offset0:128 offset1:160
	ds_write2_b32 v74, v94, v78 offset1:32
	ds_write2_b32 v74, v95, v79 offset0:128 offset1:160
	v_lshlrev_b32_e32 v64, 2, v106
	v_mov_b32_e32 v65, 0
	s_mov_b32 s16, s43
	v_or_b32_e32 v224, s16, v66
	v_mov_b32_e32 v226, s68
	v_mov_b32_e32 v227, s69
	v_mov_b32_e32 v162, s3
	v_mov_b32_e32 v163, s33
	v_cmp_gt_i32_e32 vcc, s8, v224
	v_add_u32_e32 v225, 0xffffc000, v224
	s_nop 0
	v_cndmask_b32_e32 v224, v225, v224, vcc
	v_cndmask_b32_e32 v226, v162, v226, vcc
	v_cndmask_b32_e32 v227, v163, v227, vcc
	v_mov_b32_e32 v225, 0
	v_lshlrev_b64 v[224:225], 12, v[224:225]
	v_lshl_add_u64 v[224:225], v[226:227], 0, v[224:225]
	v_lshl_add_u64 v[224:225], v[224:225], 0, s[4:5]
	v_lshl_add_u64 v[162:163], v[224:225], 0, v[64:65]
	global_load_dwordx4 v[224:227], v[162:163], off
	v_or_b32_e32 v228, s16, v67
	v_mov_b32_e32 v230, s68
	v_mov_b32_e32 v231, s69
	v_mov_b32_e32 v164, s3
	v_mov_b32_e32 v165, s33
	v_cmp_gt_i32_e32 vcc, s8, v228
	v_add_u32_e32 v229, 0xffffc000, v228
	s_nop 0
	v_cndmask_b32_e32 v228, v229, v228, vcc
	v_cndmask_b32_e32 v230, v164, v230, vcc
	v_cndmask_b32_e32 v231, v165, v231, vcc
	v_mov_b32_e32 v229, 0
	v_lshlrev_b64 v[228:229], 12, v[228:229]
	v_lshl_add_u64 v[228:229], v[230:231], 0, v[228:229]
	v_lshl_add_u64 v[228:229], v[228:229], 0, s[4:5]
	v_lshl_add_u64 v[164:165], v[228:229], 0, v[64:65]
	global_load_dwordx4 v[228:231], v[164:165], off
	v_or_b32_e32 v232, s16, v68
	v_mov_b32_e32 v234, s68
	v_mov_b32_e32 v235, s69
	v_mov_b32_e32 v166, s3
	v_mov_b32_e32 v167, s33
	v_cmp_gt_i32_e32 vcc, s8, v232
	v_add_u32_e32 v233, 0xffffc000, v232
	s_nop 0
	v_cndmask_b32_e32 v232, v233, v232, vcc
	v_cndmask_b32_e32 v234, v166, v234, vcc
	v_cndmask_b32_e32 v235, v167, v235, vcc
	v_mov_b32_e32 v233, 0
	v_lshlrev_b64 v[232:233], 12, v[232:233]
	v_lshl_add_u64 v[232:233], v[234:235], 0, v[232:233]
	v_lshl_add_u64 v[232:233], v[232:233], 0, s[4:5]
	v_lshl_add_u64 v[166:167], v[232:233], 0, v[64:65]
	global_load_dwordx4 v[232:235], v[166:167], off
	v_or_b32_e32 v236, s16, v69
	v_mov_b32_e32 v238, s68
	v_mov_b32_e32 v239, s69
	v_mov_b32_e32 v168, s3
	v_mov_b32_e32 v169, s33
	v_cmp_gt_i32_e32 vcc, s8, v236
	v_add_u32_e32 v237, 0xffffc000, v236
	s_nop 0
	v_cndmask_b32_e32 v236, v237, v236, vcc
	v_cndmask_b32_e32 v238, v168, v238, vcc
	v_cndmask_b32_e32 v239, v169, v239, vcc
	v_mov_b32_e32 v237, 0
	v_lshlrev_b64 v[236:237], 12, v[236:237]
	v_lshl_add_u64 v[236:237], v[238:239], 0, v[236:237]
	v_lshl_add_u64 v[236:237], v[236:237], 0, s[4:5]
	v_lshl_add_u64 v[168:169], v[236:237], 0, v[64:65]
	global_load_dwordx4 v[236:239], v[168:169], off
	s_add_u32 s16, s43, 96
	v_or_b32_e32 v240, s16, v66
	v_mov_b32_e32 v242, s68
	v_mov_b32_e32 v243, s69
	v_mov_b32_e32 v170, s3
	v_mov_b32_e32 v171, s33
	v_cmp_gt_i32_e32 vcc, s8, v240
	v_add_u32_e32 v241, 0xffffc000, v240
	s_nop 0
	v_cndmask_b32_e32 v240, v241, v240, vcc
	v_cndmask_b32_e32 v242, v170, v242, vcc
	v_cndmask_b32_e32 v243, v171, v243, vcc
	v_mov_b32_e32 v241, 0
	v_lshlrev_b64 v[240:241], 12, v[240:241]
	v_lshl_add_u64 v[240:241], v[242:243], 0, v[240:241]
	v_lshl_add_u64 v[240:241], v[240:241], 0, s[4:5]
	v_lshl_add_u64 v[170:171], v[240:241], 0, v[64:65]
	global_load_dwordx4 v[240:243], v[170:171], off
	v_or_b32_e32 v244, s16, v67
	v_mov_b32_e32 v246, s68
	v_mov_b32_e32 v247, s69
	v_mov_b32_e32 v172, s3
	v_mov_b32_e32 v173, s33
	v_cmp_gt_i32_e32 vcc, s8, v244
	v_add_u32_e32 v245, 0xffffc000, v244
	s_nop 0
	v_cndmask_b32_e32 v244, v245, v244, vcc
; template <int EPI, int MI>
; DI void gemm_tile(const GemmDesc& g, int tm, int tn, char* smem) {
;     ...
;       __syncthreads();
; #pragma unroll 4
;       for (int j = 0; j < 8; ++j) {
;         const int lrow = (tid >> 5) + 8 * j;
;         const int grow = m0 + (lrow >> 5) * (32 * MI) + mi * 32 + (lrow & 31);
;         const f32x4v a4 = *(const f32x4v*)(es + lrow * 128 + c4);
;         const int rg = grow < LAT ? (grow >> 11) : 8;
;         const f32x4v m4 = rg == rgA ? m4a : m4b;
;         float* rp = (grow < LAT ? g.xres + (size_t)grow * 1024 : g.hres + (size_t)(grow - LAT) * 1024) + n0 + c4;
;         f32x4v x4 = *(const f32x4v*)rp;
;         x4 += (m4 * a4) * g.coef;
;         *(f32x4v*)rp = x4;
;       }
	v_cndmask_b32_e32 v246, v172, v246, vcc
	v_cndmask_b32_e32 v247, v173, v247, vcc
	v_mov_b32_e32 v245, 0
	v_lshlrev_b64 v[244:245], 12, v[244:245]
	v_lshl_add_u64 v[244:245], v[246:247], 0, v[244:245]
	v_lshl_add_u64 v[244:245], v[244:245], 0, s[4:5]
	v_lshl_add_u64 v[172:173], v[244:245], 0, v[64:65]
	global_load_dwordx4 v[244:247], v[172:173], off
	v_or_b32_e32 v248, s16, v68
	v_mov_b32_e32 v250, s68
	v_mov_b32_e32 v251, s69
	v_mov_b32_e32 v174, s3
	v_mov_b32_e32 v175, s33
	v_cmp_gt_i32_e32 vcc, s8, v248
	v_add_u32_e32 v249, 0xffffc000, v248
	s_nop 0
	v_cndmask_b32_e32 v248, v249, v248, vcc
	v_cndmask_b32_e32 v250, v174, v250, vcc
	v_cndmask_b32_e32 v251, v175, v251, vcc
	v_mov_b32_e32 v249, 0
	v_lshlrev_b64 v[248:249], 12, v[248:249]
	v_lshl_add_u64 v[248:249], v[250:251], 0, v[248:249]
	v_lshl_add_u64 v[248:249], v[248:249], 0, s[4:5]
	v_lshl_add_u64 v[174:175], v[248:249], 0, v[64:65]
	global_load_dwordx4 v[248:251], v[174:175], off
	v_or_b32_e32 v252, s16, v69
	v_mov_b32_e32 v254, s68
	v_mov_b32_e32 v255, s69
	v_mov_b32_e32 v176, s3
	v_mov_b32_e32 v177, s33
	v_cmp_gt_i32_e32 vcc, s8, v252
	v_add_u32_e32 v253, 0xffffc000, v252
	s_nop 0
	v_cndmask_b32_e32 v252, v253, v252, vcc
	v_cndmask_b32_e32 v254, v176, v254, vcc
	v_cndmask_b32_e32 v255, v177, v255, vcc
	v_mov_b32_e32 v253, 0
	v_lshlrev_b64 v[252:253], 12, v[252:253]
	v_lshl_add_u64 v[252:253], v[254:255], 0, v[252:253]
	v_lshl_add_u64 v[252:253], v[252:253], 0, s[4:5]
	v_lshl_add_u64 v[176:177], v[252:253], 0, v[64:65]
	global_load_dwordx4 v[252:255], v[176:177], off
	s_waitcnt lgkmcnt(0)
	s_barrier
	s_waitcnt vmcnt(8)
	ds_read_b128 v[84:87], v70
	s_mov_b32 s16, s43
	s_ashr_i32 s17, s16, 11
	v_or_b32_e32 v88, s16, v66
	v_mov_b32_e32 v89, s17
	v_cmp_gt_i32_e32 vcc, s8, v88
	ds_read_b128 v[92:95], v70 offset:4096
	s_nop 0
	v_cndmask_b32_e32 v89, 8, v89, vcc
	v_cmp_eq_u32_e64 s[0:1], s15, v89
	s_nop 1
	v_cndmask_b32_e64 v89, v103, v99, s[0:1]
	v_cndmask_b32_e64 v88, v102, v98, s[0:1]
	v_cndmask_b32_e64 v91, v105, v101, s[0:1]
	v_cndmask_b32_e64 v90, v104, v100, s[0:1]
	s_waitcnt lgkmcnt(1)
	v_pk_mul_f32 v[86:87], v[86:87], v[90:91]
	v_pk_mul_f32 v[84:85], v[84:85], v[88:89]
	s_waitcnt vmcnt(7)
	v_pk_fma_f32 v[84:85], v[84:85], 0.5, v[224:225] op_sel_hi:[1,0,1]
	v_pk_fma_f32 v[86:87], v[86:87], 0.5, v[226:227] op_sel_hi:[1,0,1]
	global_store_dwordx4 v[162:163], v[84:87], off
	v_or_b32_e32 v88, s16, v67
	v_mov_b32_e32 v89, s17
	v_cmp_gt_i32_e32 vcc, s8, v88
	ds_read_b128 v[84:87], v70 offset:8192
	s_nop 0
	v_cndmask_b32_e32 v89, 8, v89, vcc
	v_cmp_eq_u32_e64 s[0:1], s15, v89
	s_nop 1
	v_cndmask_b32_e64 v89, v103, v99, s[0:1]
	v_cndmask_b32_e64 v88, v102, v98, s[0:1]
	v_cndmask_b32_e64 v91, v105, v101, s[0:1]
	v_cndmask_b32_e64 v90, v104, v100, s[0:1]
	s_waitcnt lgkmcnt(1)
	v_pk_mul_f32 v[94:95], v[94:95], v[90:91]
	v_pk_mul_f32 v[92:93], v[92:93], v[88:89]
	s_waitcnt vmcnt(7)
	v_pk_fma_f32 v[92:93], v[92:93], 0.5, v[228:229] op_sel_hi:[1,0,1]
	v_pk_fma_f32 v[94:95], v[94:95], 0.5, v[230:231] op_sel_hi:[1,0,1]
	global_store_dwordx4 v[164:165], v[92:95], off
	v_or_b32_e32 v88, s16, v68
	v_mov_b32_e32 v89, s17
	v_cmp_gt_i32_e32 vcc, s8, v88
	ds_read_b128 v[92:95], v70 offset:12288
	s_nop 0
	v_cndmask_b32_e32 v89, 8, v89, vcc
	v_cmp_eq_u32_e64 s[0:1], s15, v89
	s_nop 1
	v_cndmask_b32_e64 v89, v103, v99, s[0:1]
	v_cndmask_b32_e64 v88, v102, v98, s[0:1]
	v_cndmask_b32_e64 v91, v105, v101, s[0:1]
	v_cndmask_b32_e64 v90, v104, v100, s[0:1]
	s_waitcnt lgkmcnt(1)
	v_pk_mul_f32 v[86:87], v[86:87], v[90:91]
	v_pk_mul_f32 v[84:85], v[84:85], v[88:89]
	s_waitcnt vmcnt(7)
	v_pk_fma_f32 v[84:85], v[84:85], 0.5, v[232:233] op_sel_hi:[1,0,1]
	v_pk_fma_f32 v[86:87], v[86:87], 0.5, v[234:235] op_sel_hi:[1,0,1]
	global_store_dwordx4 v[166:167], v[84:87], off
	v_or_b32_e32 v88, s16, v69
	v_mov_b32_e32 v89, s17
	v_cmp_gt_i32_e32 vcc, s8, v88
	ds_read_b128 v[84:87], v70 offset:16384
	s_nop 0
	v_cndmask_b32_e32 v89, 8, v89, vcc
	v_cmp_eq_u32_e64 s[0:1], s15, v89
	s_nop 1
	v_cndmask_b32_e64 v89, v103, v99, s[0:1]
	v_cndmask_b32_e64 v88, v102, v98, s[0:1]
	v_cndmask_b32_e64 v91, v105, v101, s[0:1]
	v_cndmask_b32_e64 v90, v104, v100, s[0:1]
	s_waitcnt lgkmcnt(1)
	v_pk_mul_f32 v[94:95], v[94:95], v[90:91]
	v_pk_mul_f32 v[92:93], v[92:93], v[88:89]
	s_waitcnt vmcnt(7)
	v_pk_fma_f32 v[92:93], v[92:93], 0.5, v[236:237] op_sel_hi:[1,0,1]
	v_pk_fma_f32 v[94:95], v[94:95], 0.5, v[238:239] op_sel_hi:[1,0,1]
	global_store_dwordx4 v[168:169], v[92:95], off
	s_add_u32 s16, s43, 96
	s_ashr_i32 s17, s16, 11
	v_or_b32_e32 v88, s16, v66
	v_mov_b32_e32 v89, s17
	v_cmp_gt_i32_e32 vcc, s8, v88
	ds_read_b128 v[92:95], v70 offset:20480
	s_nop 0
	v_cndmask_b32_e32 v89, 8, v89, vcc
	v_cmp_eq_u32_e64 s[0:1], s15, v89
	s_nop 1
	v_cndmask_b32_e64 v89, v103, v99, s[0:1]
	v_cndmask_b32_e64 v88, v102, v98, s[0:1]
	v_cndmask_b32_e64 v91, v105, v101, s[0:1]
	v_cndmask_b32_e64 v90, v104, v100, s[0:1]
	s_waitcnt lgkmcnt(1)
	v_pk_mul_f32 v[86:87], v[86:87], v[90:91]
	v_pk_mul_f32 v[84:85], v[84:85], v[88:89]
	s_waitcnt vmcnt(7)
	v_pk_fma_f32 v[84:85], v[84:85], 0.5, v[240:241] op_sel_hi:[1,0,1]
	v_pk_fma_f32 v[86:87], v[86:87], 0.5, v[242:243] op_sel_hi:[1,0,1]
	global_store_dwordx4 v[170:171], v[84:87], off
	v_or_b32_e32 v88, s16, v67
	v_mov_b32_e32 v89, s17
	v_cmp_gt_i32_e32 vcc, s8, v88
	ds_read_b128 v[84:87], v70 offset:24576
	s_nop 0
	v_cndmask_b32_e32 v89, 8, v89, vcc
	v_cmp_eq_u32_e64 s[0:1], s15, v89
	s_nop 1
	v_cndmask_b32_e64 v89, v103, v99, s[0:1]
	v_cndmask_b32_e64 v88, v102, v98, s[0:1]
	v_cndmask_b32_e64 v91, v105, v101, s[0:1]
	v_cndmask_b32_e64 v90, v104, v100, s[0:1]
	s_waitcnt lgkmcnt(1)
; template <int EPI, int MI>
; DI void gemm_tile(const GemmDesc& g, int tm, int tn, char* smem) {
;     ...
; #pragma unroll 4
;       for (int j = 0; j < 8; ++j) {
;         const int lrow = (tid >> 5) + 8 * j;
;         const int grow = m0 + (lrow >> 5) * (32 * MI) + mi * 32 + (lrow & 31);
;         const f32x4v a4 = *(const f32x4v*)(es + lrow * 128 + c4);
;         const int rg = grow < LAT ? (grow >> 11) : 8;
;         const f32x4v m4 = rg == rgA ? m4a : m4b;
;         float* rp = (grow < LAT ? g.xres + (size_t)grow * 1024 : g.hres + (size_t)(grow - LAT) * 1024) + n0 + c4;
;         f32x4v x4 = *(const f32x4v*)rp;
;         x4 += (m4 * a4) * g.coef;
;         *(f32x4v*)rp = x4;
;       }
;       __syncthreads();
	v_pk_mul_f32 v[94:95], v[94:95], v[90:91]
	v_pk_mul_f32 v[92:93], v[92:93], v[88:89]
	s_waitcnt vmcnt(7)
	v_pk_fma_f32 v[92:93], v[92:93], 0.5, v[244:245] op_sel_hi:[1,0,1]
	v_pk_fma_f32 v[94:95], v[94:95], 0.5, v[246:247] op_sel_hi:[1,0,1]
	global_store_dwordx4 v[172:173], v[92:95], off
	v_or_b32_e32 v88, s16, v68
	v_mov_b32_e32 v89, s17
	v_cmp_gt_i32_e32 vcc, s8, v88
	ds_read_b128 v[92:95], v70 offset:28672
	s_nop 0
	v_cndmask_b32_e32 v89, 8, v89, vcc
	v_cmp_eq_u32_e64 s[0:1], s15, v89
	s_nop 1
	v_cndmask_b32_e64 v89, v103, v99, s[0:1]
	v_cndmask_b32_e64 v88, v102, v98, s[0:1]
	v_cndmask_b32_e64 v91, v105, v101, s[0:1]
	v_cndmask_b32_e64 v90, v104, v100, s[0:1]
	s_waitcnt lgkmcnt(1)
	v_pk_mul_f32 v[86:87], v[86:87], v[90:91]
	v_pk_mul_f32 v[84:85], v[84:85], v[88:89]
	s_waitcnt vmcnt(7)
	v_pk_fma_f32 v[84:85], v[84:85], 0.5, v[248:249] op_sel_hi:[1,0,1]
	v_pk_fma_f32 v[86:87], v[86:87], 0.5, v[250:251] op_sel_hi:[1,0,1]
	global_store_dwordx4 v[174:175], v[84:87], off
	v_or_b32_e32 v88, s16, v69
	v_mov_b32_e32 v89, s17
	v_cmp_gt_i32_e32 vcc, s8, v88
	s_nop 1
	v_cndmask_b32_e32 v89, 8, v89, vcc
	v_cmp_eq_u32_e64 s[0:1], s15, v89
	s_nop 1
	v_cndmask_b32_e64 v89, v103, v99, s[0:1]
	v_cndmask_b32_e64 v88, v102, v98, s[0:1]
	v_cndmask_b32_e64 v91, v105, v101, s[0:1]
	v_cndmask_b32_e64 v90, v104, v100, s[0:1]
	s_waitcnt lgkmcnt(0)
	v_pk_mul_f32 v[94:95], v[94:95], v[90:91]
	v_pk_mul_f32 v[92:93], v[92:93], v[88:89]
	s_waitcnt vmcnt(7)
	v_pk_fma_f32 v[92:93], v[92:93], 0.5, v[252:253] op_sel_hi:[1,0,1]
	v_pk_fma_f32 v[94:95], v[94:95], 0.5, v[254:255] op_sel_hi:[1,0,1]
	global_store_dwordx4 v[176:177], v[92:95], off
	s_add_u32 s16, s43, 32
	v_or_b32_e32 v224, s16, v66
	v_mov_b32_e32 v226, s68
	v_mov_b32_e32 v227, s69
	v_mov_b32_e32 v162, s3
	v_mov_b32_e32 v163, s33
	v_cmp_gt_i32_e32 vcc, s8, v224
	v_add_u32_e32 v225, 0xffffc000, v224
	s_nop 0
	v_cndmask_b32_e32 v224, v225, v224, vcc
	v_cndmask_b32_e32 v226, v162, v226, vcc
	v_cndmask_b32_e32 v227, v163, v227, vcc
	v_mov_b32_e32 v225, 0
	v_lshlrev_b64 v[224:225], 12, v[224:225]
	v_lshl_add_u64 v[224:225], v[226:227], 0, v[224:225]
	v_lshl_add_u64 v[224:225], v[224:225], 0, s[4:5]
	v_lshl_add_u64 v[162:163], v[224:225], 0, v[64:65]
	global_load_dwordx4 v[224:227], v[162:163], off
	v_or_b32_e32 v228, s16, v67
	v_mov_b32_e32 v230, s68
	v_mov_b32_e32 v231, s69
	v_mov_b32_e32 v164, s3
	v_mov_b32_e32 v165, s33
	v_cmp_gt_i32_e32 vcc, s8, v228
	v_add_u32_e32 v229, 0xffffc000, v228
	s_nop 0
	v_cndmask_b32_e32 v228, v229, v228, vcc
	v_cndmask_b32_e32 v230, v164, v230, vcc
	v_cndmask_b32_e32 v231, v165, v231, vcc
	v_mov_b32_e32 v229, 0
	v_lshlrev_b64 v[228:229], 12, v[228:229]
	v_lshl_add_u64 v[228:229], v[230:231], 0, v[228:229]
	v_lshl_add_u64 v[228:229], v[228:229], 0, s[4:5]
	v_lshl_add_u64 v[164:165], v[228:229], 0, v[64:65]
	global_load_dwordx4 v[228:231], v[164:165], off
	v_or_b32_e32 v232, s16, v68
	v_mov_b32_e32 v234, s68
	v_mov_b32_e32 v235, s69
	v_mov_b32_e32 v166, s3
	v_mov_b32_e32 v167, s33
	v_cmp_gt_i32_e32 vcc, s8, v232
	v_add_u32_e32 v233, 0xffffc000, v232
	s_nop 0
	v_cndmask_b32_e32 v232, v233, v232, vcc
	v_cndmask_b32_e32 v234, v166, v234, vcc
	v_cndmask_b32_e32 v235, v167, v235, vcc
	v_mov_b32_e32 v233, 0
	v_lshlrev_b64 v[232:233], 12, v[232:233]
	v_lshl_add_u64 v[232:233], v[234:235], 0, v[232:233]
	v_lshl_add_u64 v[232:233], v[232:233], 0, s[4:5]
	v_lshl_add_u64 v[166:167], v[232:233], 0, v[64:65]
	global_load_dwordx4 v[232:235], v[166:167], off
	v_or_b32_e32 v236, s16, v69
	v_mov_b32_e32 v238, s68
	v_mov_b32_e32 v239, s69
	v_mov_b32_e32 v168, s3
	v_mov_b32_e32 v169, s33
	v_cmp_gt_i32_e32 vcc, s8, v236
	v_add_u32_e32 v237, 0xffffc000, v236
	s_nop 0
	v_cndmask_b32_e32 v236, v237, v236, vcc
	v_cndmask_b32_e32 v238, v168, v238, vcc
	v_cndmask_b32_e32 v239, v169, v239, vcc
	v_mov_b32_e32 v237, 0
	v_lshlrev_b64 v[236:237], 12, v[236:237]
	v_lshl_add_u64 v[236:237], v[238:239], 0, v[236:237]
	v_lshl_add_u64 v[236:237], v[236:237], 0, s[4:5]
	v_lshl_add_u64 v[168:169], v[236:237], 0, v[64:65]
	global_load_dwordx4 v[236:239], v[168:169], off
	s_add_u32 s16, s43, 128
	v_or_b32_e32 v240, s16, v66
	v_mov_b32_e32 v242, s68
	v_mov_b32_e32 v243, s69
	v_mov_b32_e32 v170, s3
	v_mov_b32_e32 v171, s33
	v_cmp_gt_i32_e32 vcc, s8, v240
	v_add_u32_e32 v241, 0xffffc000, v240
	s_nop 0
	v_cndmask_b32_e32 v240, v241, v240, vcc
	v_cndmask_b32_e32 v242, v170, v242, vcc
	v_cndmask_b32_e32 v243, v171, v243, vcc
	v_mov_b32_e32 v241, 0
	v_lshlrev_b64 v[240:241], 12, v[240:241]
	v_lshl_add_u64 v[240:241], v[242:243], 0, v[240:241]
	v_lshl_add_u64 v[240:241], v[240:241], 0, s[4:5]
	v_lshl_add_u64 v[170:171], v[240:241], 0, v[64:65]
	global_load_dwordx4 v[240:243], v[170:171], off
	v_or_b32_e32 v244, s16, v67
	v_mov_b32_e32 v246, s68
	v_mov_b32_e32 v247, s69
	v_mov_b32_e32 v172, s3
	v_mov_b32_e32 v173, s33
	v_cmp_gt_i32_e32 vcc, s8, v244
	v_add_u32_e32 v245, 0xffffc000, v244
	s_nop 0
	v_cndmask_b32_e32 v244, v245, v244, vcc
	v_cndmask_b32_e32 v246, v172, v246, vcc
	v_cndmask_b32_e32 v247, v173, v247, vcc
	v_mov_b32_e32 v245, 0
	v_lshlrev_b64 v[244:245], 12, v[244:245]
	v_lshl_add_u64 v[244:245], v[246:247], 0, v[244:245]
	v_lshl_add_u64 v[244:245], v[244:245], 0, s[4:5]
	v_lshl_add_u64 v[172:173], v[244:245], 0, v[64:65]
	global_load_dwordx4 v[244:247], v[172:173], off
	v_or_b32_e32 v248, s16, v68
	v_mov_b32_e32 v250, s68
	v_mov_b32_e32 v251, s69
	v_mov_b32_e32 v174, s3
	v_mov_b32_e32 v175, s33
	v_cmp_gt_i32_e32 vcc, s8, v248
	v_add_u32_e32 v249, 0xffffc000, v248
	s_nop 0
	v_cndmask_b32_e32 v248, v249, v248, vcc
	v_cndmask_b32_e32 v250, v174, v250, vcc
	v_cndmask_b32_e32 v251, v175, v251, vcc
	v_mov_b32_e32 v249, 0
	v_lshlrev_b64 v[248:249], 12, v[248:249]
	v_lshl_add_u64 v[248:249], v[250:251], 0, v[248:249]
	v_lshl_add_u64 v[248:249], v[248:249], 0, s[4:5]
	v_lshl_add_u64 v[174:175], v[248:249], 0, v[64:65]
	global_load_dwordx4 v[248:251], v[174:175], off
	v_or_b32_e32 v252, s16, v69
	v_mov_b32_e32 v254, s68
	v_mov_b32_e32 v255, s69
	v_mov_b32_e32 v176, s3
	v_mov_b32_e32 v177, s33
	v_cmp_gt_i32_e32 vcc, s8, v252
	v_add_u32_e32 v253, 0xffffc000, v252
	s_nop 0
	v_cndmask_b32_e32 v252, v253, v252, vcc
	v_cndmask_b32_e32 v254, v176, v254, vcc
	v_cndmask_b32_e32 v255, v177, v255, vcc
	v_mov_b32_e32 v253, 0
	v_lshlrev_b64 v[252:253], 12, v[252:253]
	v_lshl_add_u64 v[252:253], v[254:255], 0, v[252:253]
	v_lshl_add_u64 v[252:253], v[252:253], 0, s[4:5]
	v_lshl_add_u64 v[176:177], v[252:253], 0, v[64:65]
	global_load_dwordx4 v[252:255], v[176:177], off
	s_barrier
; template <int EPI, int MI>
; DI void gemm_tile(const GemmDesc& g, int tm, int tn, char* smem) {
;     ...
;     for (int mi = 0; mi < MI; ++mi) {
; #pragma unroll
;       for (int ni = 0; ni < 2; ++ni)
; #pragma unroll
;         for (int i = 0; i < 16; ++i) {
;           const int lrow = wm * 32 + (i & 3) + 8 * (i >> 2) + 4 * hh;
;           es[lrow * 128 + wn * 64 + ni * 32 + r] = acc[mi][ni][i];
;         }
;       __syncthreads();
; #pragma unroll 4
;       for (int j = 0; j < 8; ++j) {
;         const int lrow = (tid >> 5) + 8 * j;
;         const int grow = m0 + (lrow >> 5) * (32 * MI) + mi * 32 + (lrow & 31);
;         const f32x4v a4 = *(const f32x4v*)(es + lrow * 128 + c4);
;         const int rg = grow < LAT ? (grow >> 11) : 8;
;         const f32x4v m4 = rg == rgA ? m4a : m4b;
;         float* rp = (grow < LAT ? g.xres + (size_t)grow * 1024 : g.hres + (size_t)(grow - LAT) * 1024) + n0 + c4;
;         f32x4v x4 = *(const f32x4v*)rp;
;         x4 += (m4 * a4) * g.coef;
;         *(f32x4v*)rp = x4;
;       }
	ds_write2_b32 v107, v48, v32 offset1:32
	ds_write2_b32 v107, v49, v33 offset0:128 offset1:160
	ds_write2_b32 v80, v50, v34 offset1:32
	ds_write2_b32 v80, v51, v35 offset0:128 offset1:160
	ds_write2_b32 v81, v52, v36 offset1:32
	ds_write2_b32 v81, v53, v37 offset0:128 offset1:160
	ds_write2_b32 v82, v54, v38 offset1:32
	ds_write2_b32 v82, v55, v39 offset0:128 offset1:160
	ds_write2_b32 v71, v56, v40 offset1:32
	ds_write2_b32 v71, v57, v41 offset0:128 offset1:160
	ds_write2_b32 v72, v58, v42 offset1:32
	ds_write2_b32 v72, v59, v43 offset0:128 offset1:160
	ds_write2_b32 v73, v60, v44 offset1:32
	ds_write2_b32 v73, v61, v45 offset0:128 offset1:160
	ds_write2_b32 v74, v62, v46 offset1:32
	ds_write2_b32 v74, v63, v47 offset0:128 offset1:160
	s_or_b32 s16, s43, 32
	s_mov_b32 s17, 0
	v_mov_b32_e32 v32, v97
	s_waitcnt lgkmcnt(0)
	s_barrier
	ds_read_b128 v[84:87], v70
	s_add_u32 s16, s43, 32
	s_ashr_i32 s17, s16, 11
	v_or_b32_e32 v88, s16, v66
	v_mov_b32_e32 v89, s17
	v_cmp_gt_i32_e32 vcc, s8, v88
	ds_read_b128 v[92:95], v70 offset:4096
	s_nop 0
	v_cndmask_b32_e32 v89, 8, v89, vcc
	v_cmp_eq_u32_e64 s[0:1], s15, v89
	s_nop 1
	v_cndmask_b32_e64 v89, v103, v99, s[0:1]
	v_cndmask_b32_e64 v88, v102, v98, s[0:1]
	v_cndmask_b32_e64 v91, v105, v101, s[0:1]
	v_cndmask_b32_e64 v90, v104, v100, s[0:1]
	s_waitcnt lgkmcnt(1)
	v_pk_mul_f32 v[86:87], v[86:87], v[90:91]
	v_pk_mul_f32 v[84:85], v[84:85], v[88:89]
	s_waitcnt vmcnt(7)
	v_pk_fma_f32 v[84:85], v[84:85], 0.5, v[224:225] op_sel_hi:[1,0,1]
	v_pk_fma_f32 v[86:87], v[86:87], 0.5, v[226:227] op_sel_hi:[1,0,1]
	global_store_dwordx4 v[162:163], v[84:87], off
	v_or_b32_e32 v88, s16, v67
	v_mov_b32_e32 v89, s17
	v_cmp_gt_i32_e32 vcc, s8, v88
	ds_read_b128 v[84:87], v70 offset:8192
	s_nop 0
	v_cndmask_b32_e32 v89, 8, v89, vcc
	v_cmp_eq_u32_e64 s[0:1], s15, v89
	s_nop 1
	v_cndmask_b32_e64 v89, v103, v99, s[0:1]
	v_cndmask_b32_e64 v88, v102, v98, s[0:1]
	v_cndmask_b32_e64 v91, v105, v101, s[0:1]
	v_cndmask_b32_e64 v90, v104, v100, s[0:1]
	s_waitcnt lgkmcnt(1)
	v_pk_mul_f32 v[94:95], v[94:95], v[90:91]
	v_pk_mul_f32 v[92:93], v[92:93], v[88:89]
	s_waitcnt vmcnt(7)
	v_pk_fma_f32 v[92:93], v[92:93], 0.5, v[228:229] op_sel_hi:[1,0,1]
	v_pk_fma_f32 v[94:95], v[94:95], 0.5, v[230:231] op_sel_hi:[1,0,1]
	global_store_dwordx4 v[164:165], v[92:95], off
	v_or_b32_e32 v88, s16, v68
	v_mov_b32_e32 v89, s17
	v_cmp_gt_i32_e32 vcc, s8, v88
	ds_read_b128 v[92:95], v70 offset:12288
	s_nop 0
	v_cndmask_b32_e32 v89, 8, v89, vcc
	v_cmp_eq_u32_e64 s[0:1], s15, v89
	s_nop 1
	v_cndmask_b32_e64 v89, v103, v99, s[0:1]
	v_cndmask_b32_e64 v88, v102, v98, s[0:1]
	v_cndmask_b32_e64 v91, v105, v101, s[0:1]
	v_cndmask_b32_e64 v90, v104, v100, s[0:1]
	s_waitcnt lgkmcnt(1)
	v_pk_mul_f32 v[86:87], v[86:87], v[90:91]
	v_pk_mul_f32 v[84:85], v[84:85], v[88:89]
	s_waitcnt vmcnt(7)
	v_pk_fma_f32 v[84:85], v[84:85], 0.5, v[232:233] op_sel_hi:[1,0,1]
	v_pk_fma_f32 v[86:87], v[86:87], 0.5, v[234:235] op_sel_hi:[1,0,1]
	global_store_dwordx4 v[166:167], v[84:87], off
	v_or_b32_e32 v88, s16, v69
	v_mov_b32_e32 v89, s17
	v_cmp_gt_i32_e32 vcc, s8, v88
	ds_read_b128 v[84:87], v70 offset:16384
	s_nop 0
	v_cndmask_b32_e32 v89, 8, v89, vcc
	v_cmp_eq_u32_e64 s[0:1], s15, v89
	s_nop 1
	v_cndmask_b32_e64 v89, v103, v99, s[0:1]
	v_cndmask_b32_e64 v88, v102, v98, s[0:1]
	v_cndmask_b32_e64 v91, v105, v101, s[0:1]
	v_cndmask_b32_e64 v90, v104, v100, s[0:1]
	s_waitcnt lgkmcnt(1)
	v_pk_mul_f32 v[94:95], v[94:95], v[90:91]
	v_pk_mul_f32 v[92:93], v[92:93], v[88:89]
	s_waitcnt vmcnt(7)
	v_pk_fma_f32 v[92:93], v[92:93], 0.5, v[236:237] op_sel_hi:[1,0,1]
	v_pk_fma_f32 v[94:95], v[94:95], 0.5, v[238:239] op_sel_hi:[1,0,1]
	global_store_dwordx4 v[168:169], v[92:95], off
	s_add_u32 s16, s43, 128
	s_ashr_i32 s17, s16, 11
	v_or_b32_e32 v88, s16, v66
	v_mov_b32_e32 v89, s17
	v_cmp_gt_i32_e32 vcc, s8, v88
	ds_read_b128 v[92:95], v70 offset:20480
	s_nop 0
	v_cndmask_b32_e32 v89, 8, v89, vcc
	v_cmp_eq_u32_e64 s[0:1], s15, v89
	s_nop 1
	v_cndmask_b32_e64 v89, v103, v99, s[0:1]
	v_cndmask_b32_e64 v88, v102, v98, s[0:1]
	v_cndmask_b32_e64 v91, v105, v101, s[0:1]
	v_cndmask_b32_e64 v90, v104, v100, s[0:1]
	s_waitcnt lgkmcnt(1)
	v_pk_mul_f32 v[86:87], v[86:87], v[90:91]
	v_pk_mul_f32 v[84:85], v[84:85], v[88:89]
	s_waitcnt vmcnt(7)
	v_pk_fma_f32 v[84:85], v[84:85], 0.5, v[240:241] op_sel_hi:[1,0,1]
	v_pk_fma_f32 v[86:87], v[86:87], 0.5, v[242:243] op_sel_hi:[1,0,1]
	global_store_dwordx4 v[170:171], v[84:87], off
	v_or_b32_e32 v88, s16, v67
	v_mov_b32_e32 v89, s17
	v_cmp_gt_i32_e32 vcc, s8, v88
	ds_read_b128 v[84:87], v70 offset:24576
	s_nop 0
	v_cndmask_b32_e32 v89, 8, v89, vcc
	v_cmp_eq_u32_e64 s[0:1], s15, v89
	s_nop 1
	v_cndmask_b32_e64 v89, v103, v99, s[0:1]
	v_cndmask_b32_e64 v88, v102, v98, s[0:1]
	v_cndmask_b32_e64 v91, v105, v101, s[0:1]
	v_cndmask_b32_e64 v90, v104, v100, s[0:1]
	s_waitcnt lgkmcnt(1)
	v_pk_mul_f32 v[94:95], v[94:95], v[90:91]
	v_pk_mul_f32 v[92:93], v[92:93], v[88:89]
	s_waitcnt vmcnt(7)
	v_pk_fma_f32 v[92:93], v[92:93], 0.5, v[244:245] op_sel_hi:[1,0,1]
	v_pk_fma_f32 v[94:95], v[94:95], 0.5, v[246:247] op_sel_hi:[1,0,1]
	global_store_dwordx4 v[172:173], v[92:95], off
	v_or_b32_e32 v88, s16, v68
	v_mov_b32_e32 v89, s17
	v_cmp_gt_i32_e32 vcc, s8, v88
	ds_read_b128 v[92:95], v70 offset:28672
	s_nop 0
	v_cndmask_b32_e32 v89, 8, v89, vcc
	v_cmp_eq_u32_e64 s[0:1], s15, v89
	s_nop 1
	v_cndmask_b32_e64 v89, v103, v99, s[0:1]
	v_cndmask_b32_e64 v88, v102, v98, s[0:1]
	v_cndmask_b32_e64 v91, v105, v101, s[0:1]
	v_cndmask_b32_e64 v90, v104, v100, s[0:1]
	s_waitcnt lgkmcnt(1)
	v_pk_mul_f32 v[86:87], v[86:87], v[90:91]
	v_pk_mul_f32 v[84:85], v[84:85], v[88:89]
	s_waitcnt vmcnt(7)
; template <int EPI, int MI>
; DI void gemm_tile(const GemmDesc& g, int tm, int tn, char* smem) {
;     ...
; #pragma unroll 4
;       for (int j = 0; j < 8; ++j) {
;         const int lrow = (tid >> 5) + 8 * j;
;         const int grow = m0 + (lrow >> 5) * (32 * MI) + mi * 32 + (lrow & 31);
;         const f32x4v a4 = *(const f32x4v*)(es + lrow * 128 + c4);
;         const int rg = grow < LAT ? (grow >> 11) : 8;
;         const f32x4v m4 = rg == rgA ? m4a : m4b;
;         float* rp = (grow < LAT ? g.xres + (size_t)grow * 1024 : g.hres + (size_t)(grow - LAT) * 1024) + n0 + c4;
;         f32x4v x4 = *(const f32x4v*)rp;
;         x4 += (m4 * a4) * g.coef;
;         *(f32x4v*)rp = x4;
;       }
;       __syncthreads();
	v_pk_fma_f32 v[84:85], v[84:85], 0.5, v[248:249] op_sel_hi:[1,0,1]
	v_pk_fma_f32 v[86:87], v[86:87], 0.5, v[250:251] op_sel_hi:[1,0,1]
	global_store_dwordx4 v[174:175], v[84:87], off
	v_or_b32_e32 v88, s16, v69
	v_mov_b32_e32 v89, s17
	v_cmp_gt_i32_e32 vcc, s8, v88
	s_nop 1
	v_cndmask_b32_e32 v89, 8, v89, vcc
	v_cmp_eq_u32_e64 s[0:1], s15, v89
	s_nop 1
	v_cndmask_b32_e64 v89, v103, v99, s[0:1]
	v_cndmask_b32_e64 v88, v102, v98, s[0:1]
	v_cndmask_b32_e64 v91, v105, v101, s[0:1]
	v_cndmask_b32_e64 v90, v104, v100, s[0:1]
	s_waitcnt lgkmcnt(0)
	v_pk_mul_f32 v[94:95], v[94:95], v[90:91]
	v_pk_mul_f32 v[92:93], v[92:93], v[88:89]
	s_waitcnt vmcnt(7)
	v_pk_fma_f32 v[92:93], v[92:93], 0.5, v[252:253] op_sel_hi:[1,0,1]
	v_pk_fma_f32 v[94:95], v[94:95], 0.5, v[254:255] op_sel_hi:[1,0,1]
	global_store_dwordx4 v[176:177], v[92:95], off
	s_add_u32 s16, s43, 64
	v_or_b32_e32 v224, s16, v66
	v_mov_b32_e32 v226, s68
	v_mov_b32_e32 v227, s69
	v_mov_b32_e32 v162, s3
	v_mov_b32_e32 v163, s33
	v_cmp_gt_i32_e32 vcc, s8, v224
	v_add_u32_e32 v225, 0xffffc000, v224
	s_nop 0
	v_cndmask_b32_e32 v224, v225, v224, vcc
	v_cndmask_b32_e32 v226, v162, v226, vcc
	v_cndmask_b32_e32 v227, v163, v227, vcc
	v_mov_b32_e32 v225, 0
	v_lshlrev_b64 v[224:225], 12, v[224:225]
	v_lshl_add_u64 v[224:225], v[226:227], 0, v[224:225]
	v_lshl_add_u64 v[224:225], v[224:225], 0, s[4:5]
	v_lshl_add_u64 v[162:163], v[224:225], 0, v[64:65]
	global_load_dwordx4 v[224:227], v[162:163], off
	v_or_b32_e32 v228, s16, v67
	v_mov_b32_e32 v230, s68
	v_mov_b32_e32 v231, s69
	v_mov_b32_e32 v164, s3
	v_mov_b32_e32 v165, s33
	v_cmp_gt_i32_e32 vcc, s8, v228
	v_add_u32_e32 v229, 0xffffc000, v228
	s_nop 0
	v_cndmask_b32_e32 v228, v229, v228, vcc
	v_cndmask_b32_e32 v230, v164, v230, vcc
	v_cndmask_b32_e32 v231, v165, v231, vcc
	v_mov_b32_e32 v229, 0
	v_lshlrev_b64 v[228:229], 12, v[228:229]
	v_lshl_add_u64 v[228:229], v[230:231], 0, v[228:229]
	v_lshl_add_u64 v[228:229], v[228:229], 0, s[4:5]
	v_lshl_add_u64 v[164:165], v[228:229], 0, v[64:65]
	global_load_dwordx4 v[228:231], v[164:165], off
	v_or_b32_e32 v232, s16, v68
	v_mov_b32_e32 v234, s68
	v_mov_b32_e32 v235, s69
	v_mov_b32_e32 v166, s3
	v_mov_b32_e32 v167, s33
	v_cmp_gt_i32_e32 vcc, s8, v232
	v_add_u32_e32 v233, 0xffffc000, v232
	s_nop 0
	v_cndmask_b32_e32 v232, v233, v232, vcc
	v_cndmask_b32_e32 v234, v166, v234, vcc
	v_cndmask_b32_e32 v235, v167, v235, vcc
	v_mov_b32_e32 v233, 0
	v_lshlrev_b64 v[232:233], 12, v[232:233]
	v_lshl_add_u64 v[232:233], v[234:235], 0, v[232:233]
	v_lshl_add_u64 v[232:233], v[232:233], 0, s[4:5]
	v_lshl_add_u64 v[166:167], v[232:233], 0, v[64:65]
	global_load_dwordx4 v[232:235], v[166:167], off
	v_or_b32_e32 v236, s16, v69
	v_mov_b32_e32 v238, s68
	v_mov_b32_e32 v239, s69
	v_mov_b32_e32 v168, s3
	v_mov_b32_e32 v169, s33
	v_cmp_gt_i32_e32 vcc, s8, v236
	v_add_u32_e32 v237, 0xffffc000, v236
	s_nop 0
	v_cndmask_b32_e32 v236, v237, v236, vcc
	v_cndmask_b32_e32 v238, v168, v238, vcc
	v_cndmask_b32_e32 v239, v169, v239, vcc
	v_mov_b32_e32 v237, 0
	v_lshlrev_b64 v[236:237], 12, v[236:237]
	v_lshl_add_u64 v[236:237], v[238:239], 0, v[236:237]
	v_lshl_add_u64 v[236:237], v[236:237], 0, s[4:5]
	v_lshl_add_u64 v[168:169], v[236:237], 0, v[64:65]
	global_load_dwordx4 v[236:239], v[168:169], off
	s_add_u32 s16, s43, 160
	v_or_b32_e32 v240, s16, v66
	v_mov_b32_e32 v242, s68
	v_mov_b32_e32 v243, s69
	v_mov_b32_e32 v170, s3
	v_mov_b32_e32 v171, s33
	v_cmp_gt_i32_e32 vcc, s8, v240
	v_add_u32_e32 v241, 0xffffc000, v240
	s_nop 0
	v_cndmask_b32_e32 v240, v241, v240, vcc
	v_cndmask_b32_e32 v242, v170, v242, vcc
	v_cndmask_b32_e32 v243, v171, v243, vcc
	v_mov_b32_e32 v241, 0
	v_lshlrev_b64 v[240:241], 12, v[240:241]
	v_lshl_add_u64 v[240:241], v[242:243], 0, v[240:241]
	v_lshl_add_u64 v[240:241], v[240:241], 0, s[4:5]
	v_lshl_add_u64 v[170:171], v[240:241], 0, v[64:65]
	global_load_dwordx4 v[240:243], v[170:171], off
	v_or_b32_e32 v244, s16, v67
	v_mov_b32_e32 v246, s68
	v_mov_b32_e32 v247, s69
	v_mov_b32_e32 v172, s3
	v_mov_b32_e32 v173, s33
	v_cmp_gt_i32_e32 vcc, s8, v244
	v_add_u32_e32 v245, 0xffffc000, v244
	s_nop 0
	v_cndmask_b32_e32 v244, v245, v244, vcc
	v_cndmask_b32_e32 v246, v172, v246, vcc
	v_cndmask_b32_e32 v247, v173, v247, vcc
	v_mov_b32_e32 v245, 0
	v_lshlrev_b64 v[244:245], 12, v[244:245]
	v_lshl_add_u64 v[244:245], v[246:247], 0, v[244:245]
	v_lshl_add_u64 v[244:245], v[244:245], 0, s[4:5]
	v_lshl_add_u64 v[172:173], v[244:245], 0, v[64:65]
	global_load_dwordx4 v[244:247], v[172:173], off
	v_or_b32_e32 v248, s16, v68
	v_mov_b32_e32 v250, s68
	v_mov_b32_e32 v251, s69
	v_mov_b32_e32 v174, s3
	v_mov_b32_e32 v175, s33
	v_cmp_gt_i32_e32 vcc, s8, v248
	v_add_u32_e32 v249, 0xffffc000, v248
	s_nop 0
	v_cndmask_b32_e32 v248, v249, v248, vcc
	v_cndmask_b32_e32 v250, v174, v250, vcc
	v_cndmask_b32_e32 v251, v175, v251, vcc
	v_mov_b32_e32 v249, 0
	v_lshlrev_b64 v[248:249], 12, v[248:249]
	v_lshl_add_u64 v[248:249], v[250:251], 0, v[248:249]
	v_lshl_add_u64 v[248:249], v[248:249], 0, s[4:5]
	v_lshl_add_u64 v[174:175], v[248:249], 0, v[64:65]
	global_load_dwordx4 v[248:251], v[174:175], off
	v_or_b32_e32 v252, s16, v69
	v_mov_b32_e32 v254, s68
	v_mov_b32_e32 v255, s69
	v_mov_b32_e32 v176, s3
	v_mov_b32_e32 v177, s33
	v_cmp_gt_i32_e32 vcc, s8, v252
	v_add_u32_e32 v253, 0xffffc000, v252
	s_nop 0
	v_cndmask_b32_e32 v252, v253, v252, vcc
	v_cndmask_b32_e32 v254, v176, v254, vcc
	v_cndmask_b32_e32 v255, v177, v255, vcc
	v_mov_b32_e32 v253, 0
	v_lshlrev_b64 v[252:253], 12, v[252:253]
	v_lshl_add_u64 v[252:253], v[254:255], 0, v[252:253]
	v_lshl_add_u64 v[252:253], v[252:253], 0, s[4:5]
	v_lshl_add_u64 v[176:177], v[252:253], 0, v[64:65]
	global_load_dwordx4 v[252:255], v[176:177], off
	s_add_i32 s43, s43, 64
	s_mov_b32 s16, 0
	s_barrier
; template <int EPI, int MI>
; DI void gemm_tile(const GemmDesc& g, int tm, int tn, char* smem) {
;     ...
;     for (int mi = 0; mi < MI; ++mi) {
; #pragma unroll
;       for (int ni = 0; ni < 2; ++ni)
; #pragma unroll
;         for (int i = 0; i < 16; ++i) {
;           const int lrow = wm * 32 + (i & 3) + 8 * (i >> 2) + 4 * hh;
;           es[lrow * 128 + wn * 64 + ni * 32 + r] = acc[mi][ni][i];
;         }
;       __syncthreads();
; #pragma unroll 4
;       for (int j = 0; j < 8; ++j) {
;         const int lrow = (tid >> 5) + 8 * j;
;         const int grow = m0 + (lrow >> 5) * (32 * MI) + mi * 32 + (lrow & 31);
;         const f32x4v a4 = *(const f32x4v*)(es + lrow * 128 + c4);
;         const int rg = grow < LAT ? (grow >> 11) : 8;
;         const f32x4v m4 = rg == rgA ? m4a : m4b;
;         float* rp = (grow < LAT ? g.xres + (size_t)grow * 1024 : g.hres + (size_t)(grow - LAT) * 1024) + n0 + c4;
;         f32x4v x4 = *(const f32x4v*)rp;
;         x4 += (m4 * a4) * g.coef;
;         *(f32x4v*)rp = x4;
;       }
;       __syncthreads();
; template <int EPI, int MI>
; DI void gemm_phase(const GemmDesc& g, char* smem, int vb, int nvb) {
;     ...
;   for (int q = start; q < local; q += step) {
;     const int mg = q / per;
;     const int rem = q - mg * per;
;     const int tn = rem / PM;
;     const int tm = mbase + mg * PM + (rem - tn * PM);
;     gemm_tile<EPI, MI>(g, tm, tn, smem);
	ds_write2_b32 v107, v16, v0 offset1:32
	ds_write2_b32 v107, v17, v1 offset0:128 offset1:160
	ds_write2_b32 v80, v18, v2 offset1:32
	ds_write2_b32 v80, v19, v3 offset0:128 offset1:160
	ds_write2_b32 v81, v20, v4 offset1:32
	ds_write2_b32 v81, v21, v5 offset0:128 offset1:160
	ds_write2_b32 v82, v22, v6 offset1:32
	ds_write2_b32 v82, v23, v7 offset0:128 offset1:160
	ds_write2_b32 v71, v24, v8 offset1:32
	ds_write2_b32 v71, v25, v9 offset0:128 offset1:160
	ds_write2_b32 v72, v26, v10 offset1:32
	ds_write2_b32 v72, v27, v11 offset0:128 offset1:160
	ds_write2_b32 v73, v28, v12 offset1:32
	ds_write2_b32 v73, v29, v13 offset0:128 offset1:160
	ds_write2_b32 v74, v30, v14 offset1:32
	ds_write2_b32 v74, v31, v15 offset0:128 offset1:160
	s_waitcnt lgkmcnt(0)
	s_barrier
	ds_read_b128 v[84:87], v70
	s_mov_b32 s16, s43
	s_ashr_i32 s17, s16, 11
	v_or_b32_e32 v88, s16, v66
	v_mov_b32_e32 v89, s17
	v_cmp_gt_i32_e32 vcc, s8, v88
	ds_read_b128 v[92:95], v70 offset:4096
	s_nop 0
	v_cndmask_b32_e32 v89, 8, v89, vcc
	v_cmp_eq_u32_e64 s[0:1], s15, v89
	s_nop 1
	v_cndmask_b32_e64 v89, v103, v99, s[0:1]
	v_cndmask_b32_e64 v88, v102, v98, s[0:1]
	v_cndmask_b32_e64 v91, v105, v101, s[0:1]
	v_cndmask_b32_e64 v90, v104, v100, s[0:1]
	s_waitcnt lgkmcnt(1)
	v_pk_mul_f32 v[86:87], v[86:87], v[90:91]
	v_pk_mul_f32 v[84:85], v[84:85], v[88:89]
	s_waitcnt vmcnt(7)
	v_pk_fma_f32 v[84:85], v[84:85], 0.5, v[224:225] op_sel_hi:[1,0,1]
	v_pk_fma_f32 v[86:87], v[86:87], 0.5, v[226:227] op_sel_hi:[1,0,1]
	global_store_dwordx4 v[162:163], v[84:87], off
	v_or_b32_e32 v88, s16, v67
	v_mov_b32_e32 v89, s17
	v_cmp_gt_i32_e32 vcc, s8, v88
	ds_read_b128 v[84:87], v70 offset:8192
	s_nop 0
	v_cndmask_b32_e32 v89, 8, v89, vcc
	v_cmp_eq_u32_e64 s[0:1], s15, v89
	s_nop 1
	v_cndmask_b32_e64 v89, v103, v99, s[0:1]
	v_cndmask_b32_e64 v88, v102, v98, s[0:1]
	v_cndmask_b32_e64 v91, v105, v101, s[0:1]
	v_cndmask_b32_e64 v90, v104, v100, s[0:1]
	s_waitcnt lgkmcnt(1)
	v_pk_mul_f32 v[94:95], v[94:95], v[90:91]
	v_pk_mul_f32 v[92:93], v[92:93], v[88:89]
	s_waitcnt vmcnt(7)
	v_pk_fma_f32 v[92:93], v[92:93], 0.5, v[228:229] op_sel_hi:[1,0,1]
	v_pk_fma_f32 v[94:95], v[94:95], 0.5, v[230:231] op_sel_hi:[1,0,1]
	global_store_dwordx4 v[164:165], v[92:95], off
	v_or_b32_e32 v88, s16, v68
	v_mov_b32_e32 v89, s17
	v_cmp_gt_i32_e32 vcc, s8, v88
	ds_read_b128 v[92:95], v70 offset:12288
	s_nop 0
	v_cndmask_b32_e32 v89, 8, v89, vcc
	v_cmp_eq_u32_e64 s[0:1], s15, v89
	s_nop 1
	v_cndmask_b32_e64 v89, v103, v99, s[0:1]
	v_cndmask_b32_e64 v88, v102, v98, s[0:1]
	v_cndmask_b32_e64 v91, v105, v101, s[0:1]
	v_cndmask_b32_e64 v90, v104, v100, s[0:1]
	s_waitcnt lgkmcnt(1)
	v_pk_mul_f32 v[86:87], v[86:87], v[90:91]
	v_pk_mul_f32 v[84:85], v[84:85], v[88:89]
	s_waitcnt vmcnt(7)
	v_pk_fma_f32 v[84:85], v[84:85], 0.5, v[232:233] op_sel_hi:[1,0,1]
	v_pk_fma_f32 v[86:87], v[86:87], 0.5, v[234:235] op_sel_hi:[1,0,1]
	global_store_dwordx4 v[166:167], v[84:87], off
	v_or_b32_e32 v88, s16, v69
	v_mov_b32_e32 v89, s17
	v_cmp_gt_i32_e32 vcc, s8, v88
	ds_read_b128 v[84:87], v70 offset:16384
	s_nop 0
	v_cndmask_b32_e32 v89, 8, v89, vcc
	v_cmp_eq_u32_e64 s[0:1], s15, v89
	s_nop 1
	v_cndmask_b32_e64 v89, v103, v99, s[0:1]
	v_cndmask_b32_e64 v88, v102, v98, s[0:1]
	v_cndmask_b32_e64 v91, v105, v101, s[0:1]
	v_cndmask_b32_e64 v90, v104, v100, s[0:1]
	s_waitcnt lgkmcnt(1)
	v_pk_mul_f32 v[94:95], v[94:95], v[90:91]
	v_pk_mul_f32 v[92:93], v[92:93], v[88:89]
	s_waitcnt vmcnt(7)
	v_pk_fma_f32 v[92:93], v[92:93], 0.5, v[236:237] op_sel_hi:[1,0,1]
	v_pk_fma_f32 v[94:95], v[94:95], 0.5, v[238:239] op_sel_hi:[1,0,1]
	global_store_dwordx4 v[168:169], v[92:95], off
	s_add_u32 s16, s43, 96
	s_ashr_i32 s17, s16, 11
	v_or_b32_e32 v88, s16, v66
	v_mov_b32_e32 v89, s17
	v_cmp_gt_i32_e32 vcc, s8, v88
	ds_read_b128 v[92:95], v70 offset:20480
	s_nop 0
	v_cndmask_b32_e32 v89, 8, v89, vcc
	v_cmp_eq_u32_e64 s[0:1], s15, v89
	s_nop 1
	v_cndmask_b32_e64 v89, v103, v99, s[0:1]
	v_cndmask_b32_e64 v88, v102, v98, s[0:1]
	v_cndmask_b32_e64 v91, v105, v101, s[0:1]
	v_cndmask_b32_e64 v90, v104, v100, s[0:1]
	s_waitcnt lgkmcnt(1)
	v_pk_mul_f32 v[86:87], v[86:87], v[90:91]
	v_pk_mul_f32 v[84:85], v[84:85], v[88:89]
	s_waitcnt vmcnt(7)
	v_pk_fma_f32 v[84:85], v[84:85], 0.5, v[240:241] op_sel_hi:[1,0,1]
	v_pk_fma_f32 v[86:87], v[86:87], 0.5, v[242:243] op_sel_hi:[1,0,1]
	global_store_dwordx4 v[170:171], v[84:87], off
	v_or_b32_e32 v88, s16, v67
	v_mov_b32_e32 v89, s17
	v_cmp_gt_i32_e32 vcc, s8, v88
	ds_read_b128 v[84:87], v70 offset:24576
	s_nop 0
	v_cndmask_b32_e32 v89, 8, v89, vcc
	v_cmp_eq_u32_e64 s[0:1], s15, v89
	s_nop 1
	v_cndmask_b32_e64 v89, v103, v99, s[0:1]
	v_cndmask_b32_e64 v88, v102, v98, s[0:1]
	v_cndmask_b32_e64 v91, v105, v101, s[0:1]
	v_cndmask_b32_e64 v90, v104, v100, s[0:1]
	s_waitcnt lgkmcnt(1)
	v_pk_mul_f32 v[94:95], v[94:95], v[90:91]
	v_pk_mul_f32 v[92:93], v[92:93], v[88:89]
	s_waitcnt vmcnt(7)
	v_pk_fma_f32 v[92:93], v[92:93], 0.5, v[244:245] op_sel_hi:[1,0,1]
	v_pk_fma_f32 v[94:95], v[94:95], 0.5, v[246:247] op_sel_hi:[1,0,1]
	global_store_dwordx4 v[172:173], v[92:95], off
	v_or_b32_e32 v88, s16, v68
	v_mov_b32_e32 v89, s17
	v_cmp_gt_i32_e32 vcc, s8, v88
	ds_read_b128 v[92:95], v70 offset:28672
	s_nop 0
	v_cndmask_b32_e32 v89, 8, v89, vcc
	v_cmp_eq_u32_e64 s[0:1], s15, v89
	s_nop 1
	v_cndmask_b32_e64 v89, v103, v99, s[0:1]
	v_cndmask_b32_e64 v88, v102, v98, s[0:1]
	v_cndmask_b32_e64 v91, v105, v101, s[0:1]
	v_cndmask_b32_e64 v90, v104, v100, s[0:1]
	s_waitcnt lgkmcnt(1)
	v_pk_mul_f32 v[86:87], v[86:87], v[90:91]
	v_pk_mul_f32 v[84:85], v[84:85], v[88:89]
	s_waitcnt vmcnt(7)
	v_pk_fma_f32 v[84:85], v[84:85], 0.5, v[248:249] op_sel_hi:[1,0,1]
	v_pk_fma_f32 v[86:87], v[86:87], 0.5, v[250:251] op_sel_hi:[1,0,1]
	global_store_dwordx4 v[174:175], v[84:87], off
	v_or_b32_e32 v88, s16, v69
	v_mov_b32_e32 v89, s17
	v_cmp_gt_i32_e32 vcc, s8, v88
	s_nop 1
	v_cndmask_b32_e32 v89, 8, v89, vcc
	v_cmp_eq_u32_e64 s[0:1], s15, v89
	s_nop 1
	v_cndmask_b32_e64 v89, v103, v99, s[0:1]
	v_cndmask_b32_e64 v88, v102, v98, s[0:1]
	v_cndmask_b32_e64 v91, v105, v101, s[0:1]
	v_cndmask_b32_e64 v90, v104, v100, s[0:1]
	s_waitcnt lgkmcnt(0)
	v_pk_mul_f32 v[94:95], v[94:95], v[90:91]
	v_pk_mul_f32 v[92:93], v[92:93], v[88:89]
	s_waitcnt vmcnt(7)
	v_pk_fma_f32 v[92:93], v[92:93], 0.5, v[252:253] op_sel_hi:[1,0,1]
	v_pk_fma_f32 v[94:95], v[94:95], 0.5, v[254:255] op_sel_hi:[1,0,1]
	global_store_dwordx4 v[176:177], v[92:95], off
	v_readlane_b32 s0, v218, 38
	s_add_i32 s42, s42, s0
	v_readlane_b32 s0, v218, 31
	s_add_i32 s39, s39, s0
	v_readlane_b32 s0, v221, 13
	s_cmp_lt_i32 s42, s0
	s_barrier
	s_cbranch_scc1 .LBB0_254

; __global__ void __launch_bounds__(NTHR, 2) mega(P p) {
	.amdhsa_kernel _Z4mega1P
		.amdhsa_group_segment_fixed_size 0
		.amdhsa_private_segment_fixed_size 0
		.amdhsa_kernarg_size 512
		.amdhsa_user_sgpr_count 2
		.amdhsa_user_sgpr_dispatch_ptr 0
		.amdhsa_user_sgpr_queue_ptr 0
		.amdhsa_user_sgpr_kernarg_segment_ptr 1
		.amdhsa_user_sgpr_dispatch_id 0
		.amdhsa_user_sgpr_kernarg_preload_length 0
		.amdhsa_user_sgpr_kernarg_preload_offset 0
		.amdhsa_user_sgpr_private_segment_size 0
		.amdhsa_uses_dynamic_stack 0
		.amdhsa_enable_private_segment 0
		.amdhsa_system_sgpr_workgroup_id_x 1
		.amdhsa_system_sgpr_workgroup_id_y 0
		.amdhsa_system_sgpr_workgroup_id_z 0
		.amdhsa_system_sgpr_workgroup_info 0
		.amdhsa_system_vgpr_workitem_id 2
		.amdhsa_next_free_vgpr 256
		.amdhsa_next_free_sgpr 102
		.amdhsa_accum_offset 256
		.amdhsa_reserve_vcc 1
		.amdhsa_float_round_mode_32 0
		.amdhsa_float_round_mode_16_64 0
		.amdhsa_float_denorm_mode_32 3
		.amdhsa_float_denorm_mode_16_64 3
		.amdhsa_dx10_clamp 1
		.amdhsa_ieee_mode 1
		.amdhsa_fp16_overflow 0
		.amdhsa_tg_split 0
		.amdhsa_exception_fp_ieee_invalid_op 0
		.amdhsa_exception_fp_denorm_src 0
		.amdhsa_exception_fp_ieee_div_zero 0
		.amdhsa_exception_fp_ieee_overflow 0
		.amdhsa_exception_fp_ieee_underflow 0
		.amdhsa_exception_fp_ieee_inexact 0
		.amdhsa_exception_int_div_zero 0
	.end_amdhsa_kernel

; __global__ void __launch_bounds__(NTHR, 2) mega(P p) {
amdhsa.kernels:
  - .agpr_count:     0
    .args:
      - .offset:         0
        .size:           256
        .value_kind:     by_value
      - .offset:         256
        .size:           4
        .value_kind:     hidden_block_count_x
      - .offset:         260
        .size:           4
        .value_kind:     hidden_block_count_y
      - .offset:         264
        .size:           4
        .value_kind:     hidden_block_count_z
      - .offset:         268
        .size:           2
        .value_kind:     hidden_group_size_x
      - .offset:         270
        .size:           2
        .value_kind:     hidden_group_size_y
      - .offset:         272
        .size:           2
        .value_kind:     hidden_group_size_z
      - .offset:         274
        .size:           2
        .value_kind:     hidden_remainder_x
      - .offset:         276
        .size:           2
        .value_kind:     hidden_remainder_y
      - .offset:         278
        .size:           2
        .value_kind:     hidden_remainder_z
      - .offset:         296
        .size:           8
        .value_kind:     hidden_global_offset_x
      - .offset:         304
        .size:           8
        .value_kind:     hidden_global_offset_y
      - .offset:         312
        .size:           8
        .value_kind:     hidden_global_offset_z
      - .offset:         320
        .size:           2
        .value_kind:     hidden_grid_dims
      - .offset:         344
        .size:           8
        .value_kind:     hidden_multigrid_sync_arg
      - .offset:         376
        .size:           4
        .value_kind:     hidden_dynamic_lds_size
    .group_segment_fixed_size: 0
    .kernarg_segment_align: 8
    .kernarg_segment_size: 512
    .language:       OpenCL C
    .language_version:
      - 2
      - 0
    .max_flat_workgroup_size: 256
    .name:           _Z4mega1P
    .private_segment_fixed_size: 0
    .sgpr_count:     108
    .sgpr_spill_count: 378
    .symbol:         _Z4mega1P.kd
    .uniform_work_group_size: 1
    .uses_dynamic_stack: false
    .vgpr_count:     256
    .vgpr_spill_count: 0
    .wavefront_size: 64
